# SWA loop: 14 packed O-rescale multiplies beside the PV MFMAs split into scalar pairs; MLA softmax: 3 redundant VALU ops per key tile removed (canonicalising maxes, zero add)
# baseline (speedup 1.0000x reference)
; #define LAS __attribute__((address_space(3)))
; __device__ __forceinline__ unsigned cvt_pk_bf16(float lo, float hi) { unsigned r; asm volatile("v_cvt_pk_bf16_f32 %0, %1, %2" : "=v"(r) : "v"(lo), "v"(hi)); return r; }
; __device__ __forceinline__ int crow(int r, int hi) { return (r & 3) + 8 * (r >> 2) + 4 * hi; }
; __device__ __forceinline__ void swa_attn_phase(LAS unsigned char* lds, const bf16_t* Q, const bf16_t* Kg, const bf16_t* VT, bf16_t* O, const float* bt2, const float* sinks, int G, int bx, const int tid) {
;     ...
;                 float mx = -1e30f;
; #pragma unroll
;                 for (int r = 0; r < 16; ++r) { const int kl = 32 * kb + crow(r, hi);
;                     const int dist = r32 + 128 - kl; const bool ok = (dist >= 0) && (dist < 128) && (t0 + 32 * qs + kl >= 0);
;                     const float bv = bs_[g * 128 + (dist & 127)];
;                     const float sv = ok ? st[r] + bv : -1e30f; st[r] = sv; mx = fmaxf(mx, sv); }
;                 mx = fmaxf(mx, __shfl_xor(mx, 32));
;                 const float mnew = fmaxf(mrun, mx), alpha = __builtin_amdgcn_exp2f(mrun - mnew); mrun = mnew;
;                 float ps = 0.f;
; #pragma unroll
;                 for (int r = 0; r < 16; ++r) { const float p = __builtin_amdgcn_exp2f(st[r] - mnew); st[r] = p; ps += p; }
;                 lrun = lrun * alpha + ps;
; #pragma unroll
;                 for (int i = 0; i < 2; ++i)
; #pragma unroll
;                     for (int r = 0; r < 16; ++r) o[i][r] *= alpha;
; #pragma unroll
;                 for (int k2 = 0; k2 < 2; ++k2) { const int rb = 8 * k2; u32x4 w;
;                     w.x = cvt_pk_bf16(st[rb + 0], st[rb + 1]); w.y = cvt_pk_bf16(st[rb + 2], st[rb + 3]); w.z = cvt_pk_bf16(st[rb + 4], st[rb + 5]); w.w = cvt_pk_bf16(st[rb + 6], st[rb + 7]);
;                     const bf16x8 pf = __builtin_bit_cast(bf16x8, w);
; #pragma unroll
;                     for (int dvb = 0; dvb < 2; ++dvb) { const LAS unsigned char* vp = vs_ + (32 * dvb + r32) * SV_STRIDE + (32 * (qs + kb) + 16 * k2 + 4 * hi) * 2;
;                         const u32x2 lo = *(const LAS u32x2*)vp, hi2 = *(const LAS u32x2*)(vp + 16); const u32x4 vw = {lo.x, lo.y, hi2.x, hi2.y};
;                         o[dvb] = __builtin_amdgcn_mfma_f32_32x32x16_bf16(__builtin_bit_cast(bf16x8, vw), pf, o[dvb], 0, 0, 0); } }
.LBB0_179:
	s_or_b64 exec, exec, s[46:47]
	s_mov_b32 s46, 0xf149f2ca
	v_max3_f32 v32, v116, s46, v115
	v_max3_f32 v32, v32, v120, v118
	v_max3_f32 v32, v32, v35, v34
	v_max3_f32 v32, v32, v37, v36
	v_max3_f32 v32, v32, v39, v38
	v_max3_f32 v32, v32, v41, v40
	v_max3_f32 v32, v32, v43, v42
	v_max3_f32 v32, v32, v45, v44
	ds_bpermute_b32 v33, v87, v32
	s_sub_i32 s59, s59, 32
	v_add_u32_e32 v111, 0x1200, v111
	v_add_u32_e32 v112, 0xffffff80, v112
	v_add_u32_e32 v110, 32, v110
	s_waitcnt lgkmcnt(0)
	v_max3_f32 v33, v114, v32, v33
	v_sub_f32_e32 v34, v34, v33
	v_sub_f32_e32 v46, v116, v33
	v_exp_f32_e32 v116, v34
	v_sub_f32_e32 v34, v37, v33
	v_exp_f32_e32 v117, v34
	v_sub_f32_e32 v34, v36, v33
	v_sub_f32_e32 v47, v115, v33
	v_sub_f32_e32 v115, v118, v33
	v_exp_f32_e32 v118, v34
	v_sub_f32_e32 v34, v39, v33
	v_exp_f32_e32 v119, v34
	v_sub_f32_e32 v34, v38, v33
	v_sub_f32_e32 v32, v114, v33
	v_sub_f32_e32 v114, v120, v33
	v_exp_f32_e32 v120, v34
	v_sub_f32_e32 v34, v41, v33
	v_exp_f32_e32 v121, v34
	v_sub_f32_e32 v34, v40, v33
	v_exp_f32_e32 v46, v46
	v_exp_f32_e32 v122, v34
	v_sub_f32_e32 v34, v43, v33
	v_exp_f32_e32 v47, v47
	v_exp_f32_e32 v123, v34
	v_sub_f32_e32 v34, v42, v33
	v_exp_f32_e32 v114, v114
	v_exp_f32_e32 v124, v34
	v_sub_f32_e32 v34, v45, v33
	v_exp_f32_e32 v115, v115
	v_sub_f32_e32 v35, v35, v33
	v_exp_f32_e32 v45, v34
	v_sub_f32_e32 v34, v44, v33
	v_exp_f32_e32 v35, v35
	v_exp_f32_e32 v44, v34
	v_add_f32_e32 v34, 0, v46
	v_add_f32_e32 v34, v47, v34
	v_add_f32_e32 v34, v114, v34
	v_add_f32_e32 v34, v115, v34
	v_add_f32_e32 v34, v35, v34
	v_cvt_pk_bf16_f32 v36, v46, v47
	v_cvt_pk_bf16_f32 v37, v114, v115
	v_cvt_pk_bf16_f32 v38, v35, v116
	v_add_u32_e32 v35, 0, v109
	v_cvt_pk_bf16_f32 v39, v117, v118
	ds_read2_b64 v[40:43], v35 offset1:2
	v_exp_f32_e32 v32, v32
	v_add_u32_e32 v46, 0x4000, v35
	v_add_f32_e32 v34, v116, v34
	v_add_f32_e32 v34, v117, v34
	v_mul_f32_e32 v16, v16, v32
	v_mul_f32_e32 v17, v17, v32
	v_mul_f32_e32 v18, v18, v32
	v_mul_f32_e32 v19, v19, v32
	v_mul_f32_e32 v20, v20, v32
	v_mul_f32_e32 v21, v21, v32
	v_mul_f32_e32 v22, v22, v32
	v_mul_f32_e32 v23, v23, v32
	v_mul_f32_e32 v24, v24, v32
	v_mul_f32_e32 v25, v25, v32
	v_mul_f32_e32 v26, v26, v32
	v_mul_f32_e32 v27, v27, v32
	v_mul_f32_e32 v28, v28, v32
	v_mul_f32_e32 v29, v29, v32
	v_mul_f32_e32 v30, v30, v32
	v_mul_f32_e32 v31, v31, v32
	v_mul_f32_e32 v0, v0, v32
	v_mul_f32_e32 v1, v1, v32
	v_mul_f32_e32 v2, v2, v32
	v_mul_f32_e32 v3, v3, v32
	s_waitcnt lgkmcnt(0)
	v_mfma_f32_32x32x16_bf16 v[16:31], v[40:43], v[36:39], v[16:31]
	ds_read2_b64 v[40:43], v46 offset0:32 offset1:34
	v_mul_f32_e64 v4, v4, v32
	v_mul_f32_e64 v5, v5, v32
	v_mul_f32_e64 v6, v6, v32
	v_mul_f32_e64 v7, v7, v32
	v_mul_f32_e32 v8, v8, v32
	v_mul_f32_e32 v9, v9, v32
	v_mul_f32_e32 v10, v10, v32
	v_mul_f32_e32 v11, v11, v32
	v_mul_f32_e32 v12, v12, v32
	v_mul_f32_e32 v13, v13, v32
	v_mul_f32_e32 v14, v14, v32
	v_mul_f32_e32 v15, v15, v32
	v_add_f32_e32 v34, v118, v34
	v_add_f32_e32 v34, v119, v34
	s_waitcnt lgkmcnt(0)
	v_mfma_f32_32x32x16_bf16 v[0:15], v[40:43], v[36:39], v[0:15]
	v_cvt_pk_bf16_f32 v36, v119, v120
	v_cvt_pk_bf16_f32 v37, v121, v122
	v_cvt_pk_bf16_f32 v38, v123, v124
	v_cvt_pk_bf16_f32 v39, v45, v44
	ds_read2_b64 v[40:43], v35 offset0:4 offset1:6
	v_add_f32_e32 v34, v120, v34
	v_add_f32_e32 v34, v121, v34
	s_waitcnt lgkmcnt(0)
	v_mfma_f32_32x32x16_bf16 v[16:31], v[40:43], v[36:39], v[16:31]
	ds_read2_b64 v[40:43], v46 offset0:36 offset1:38
	v_add_f32_e32 v34, v122, v34
	v_add_f32_e32 v34, v123, v34
	v_add_f32_e32 v34, v124, v34
	v_add_f32_e32 v34, v45, v34
	v_add_f32_e32 v34, v44, v34
	v_fmac_f32_e32 v34, v113, v32
	s_waitcnt lgkmcnt(0)
	v_mfma_f32_32x32x16_bf16 v[0:15], v[40:43], v[36:39], v[0:15]
	v_add_u32_e32 v109, 64, v109
	s_cmpk_eq_i32 s59, 0xff60
	s_cbranch_scc1 .LBB0_145
	v_mov_b32_e32 v113, v34
	v_mov_b32_e32 v114, v33
	s_branch .LBB0_147

; __device__ __forceinline__ void mla_attn_phase(LAS unsigned char* lds, const bf16_t* Q, const bf16_t* KN, const bf16_t* KR, const bf16_t* VT, bf16_t* O, int G, int bx, const int tid) {
;     ...
;                 float mx = st[0][0];
; #pragma unroll
;                 for (int r = 1; r < 16; ++r) mx = fmaxf(mx, st[0][r]);
; #pragma unroll
;                 for (int r = 0; r < 16; ++r) mx = fmaxf(mx, st[1][r]);
;                 mx = fmaxf(mx, __shfl_xor(mx, 32));
;                 const float mnew = (mx > mrun + 8.0f) ? mx : mrun;
;                 if (__any(mnew != mrun)) { const float alpha = __builtin_amdgcn_exp2f(mrun - mnew); lrun *= alpha;
; #pragma unroll
;                     for (int i = 0; i < 4; ++i)
; #pragma unroll
;                         for (int r = 0; r < 16; ++r) o[i][r] *= alpha;
;                     mrun = mnew; }
.LBB0_284:
	v_add_u32_e32 v164, s60, v231
	v_add_u32_e32 v236, v164, v230
	s_nop 4
	v_max_f32_e32 v164, v80, v81
	v_max3_f32 v164, v164, v82, v83
	v_max3_f32 v164, v164, v84, v85
	v_max3_f32 v164, v164, v86, v87
	v_max3_f32 v164, v164, v88, v89
	v_max3_f32 v164, v164, v90, v91
	v_max3_f32 v164, v164, v92, v93
	v_max3_f32 v164, v164, v94, v95
	v_max3_f32 v164, v164, v64, v65
	v_max3_f32 v164, v164, v66, v67
	v_max3_f32 v164, v164, v68, v69
	v_max3_f32 v164, v164, v70, v71
	v_max3_f32 v164, v164, v72, v73
	v_max3_f32 v164, v164, v74, v75
	v_max3_f32 v164, v164, v76, v77
	v_max3_f32 v237, v164, v78, v79
	ds_read_b128 v[176:179], v236 offset:25600
	ds_read_b128 v[172:175], v236 offset:30208
	v_mov_b32_e32 v238, v237
	ds_read_b128 v[168:171], v236 offset:34816
	ds_read_b128 v[164:167], v236 offset:39424
	v_permlane32_swap_b32_e32 v237, v238
	v_max_f32_e32 v237, v237, v238
	v_add_f32_e32 v238, 0x41000000, v235
	v_cmp_gt_f32_e32 vcc, v237, v238
	s_nop 1
	v_cndmask_b32_e32 v237, v235, v237, vcc
	v_cmp_neq_f32_e32 vcc, v237, v235
	s_cbranch_vccz .LBB0_286
	v_sub_f32_e32 v235, v235, v237
	v_exp_f32_e32 v238, v235
	v_mov_b32_e32 v235, v237
	v_pk_mul_f32 v[62:63], v[62:63], v[238:239] op_sel_hi:[1,0]
	v_pk_mul_f32 v[60:61], v[60:61], v[238:239] op_sel_hi:[1,0]
	v_pk_mul_f32 v[58:59], v[58:59], v[238:239] op_sel_hi:[1,0]
	v_pk_mul_f32 v[56:57], v[56:57], v[238:239] op_sel_hi:[1,0]
	v_pk_mul_f32 v[54:55], v[54:55], v[238:239] op_sel_hi:[1,0]
	v_pk_mul_f32 v[52:53], v[52:53], v[238:239] op_sel_hi:[1,0]
	v_pk_mul_f32 v[50:51], v[50:51], v[238:239] op_sel_hi:[1,0]
	v_pk_mul_f32 v[48:49], v[48:49], v[238:239] op_sel_hi:[1,0]
	v_pk_mul_f32 v[46:47], v[46:47], v[238:239] op_sel_hi:[1,0]
	v_pk_mul_f32 v[44:45], v[44:45], v[238:239] op_sel_hi:[1,0]
	v_pk_mul_f32 v[42:43], v[42:43], v[238:239] op_sel_hi:[1,0]
	v_pk_mul_f32 v[40:41], v[40:41], v[238:239] op_sel_hi:[1,0]
	v_pk_mul_f32 v[38:39], v[38:39], v[238:239] op_sel_hi:[1,0]
	v_pk_mul_f32 v[36:37], v[36:37], v[238:239] op_sel_hi:[1,0]
	v_pk_mul_f32 v[34:35], v[34:35], v[238:239] op_sel_hi:[1,0]
	v_pk_mul_f32 v[32:33], v[32:33], v[238:239] op_sel_hi:[1,0]
	v_pk_mul_f32 v[30:31], v[30:31], v[238:239] op_sel_hi:[1,0]
	v_pk_mul_f32 v[28:29], v[28:29], v[238:239] op_sel_hi:[1,0]
	v_pk_mul_f32 v[26:27], v[26:27], v[238:239] op_sel_hi:[1,0]
	v_pk_mul_f32 v[24:25], v[24:25], v[238:239] op_sel_hi:[1,0]
	v_pk_mul_f32 v[22:23], v[22:23], v[238:239] op_sel_hi:[1,0]
	v_pk_mul_f32 v[20:21], v[20:21], v[238:239] op_sel_hi:[1,0]
	v_pk_mul_f32 v[18:19], v[18:19], v[238:239] op_sel_hi:[1,0]
	v_pk_mul_f32 v[16:17], v[16:17], v[238:239] op_sel_hi:[1,0]
	v_pk_mul_f32 v[14:15], v[14:15], v[238:239] op_sel_hi:[1,0]
	v_pk_mul_f32 v[12:13], v[12:13], v[238:239] op_sel_hi:[1,0]
	v_pk_mul_f32 v[10:11], v[10:11], v[238:239] op_sel_hi:[1,0]
	v_pk_mul_f32 v[8:9], v[8:9], v[238:239] op_sel_hi:[1,0]
	v_pk_mul_f32 v[6:7], v[6:7], v[238:239] op_sel_hi:[1,0]
	v_pk_mul_f32 v[4:5], v[4:5], v[238:239] op_sel_hi:[1,0]
	v_pk_mul_f32 v[2:3], v[2:3], v[238:239] op_sel_hi:[1,0]
	v_pk_mul_f32 v[0:1], v[0:1], v[238:239] op_sel_hi:[1,0]
	v_mul_f32_e32 v201, v201, v238
	s_branch .LBB0_287

; __device__ __forceinline__ unsigned cvt_pk_bf16(float lo, float hi) { unsigned r; asm volatile("v_cvt_pk_bf16_f32 %0, %1, %2" : "=v"(r) : "v"(lo), "v"(hi)); return r; }
; __device__ __forceinline__ void mla_attn_phase(LAS unsigned char* lds, const bf16_t* Q, const bf16_t* KN, const bf16_t* KR, const bf16_t* VT, bf16_t* O, int G, int bx, const int tid) {
;     ...
;                 float ps = 0.f;
; #pragma unroll
;                 for (int kvh = 0; kvh < 2; ++kvh)
; #pragma unroll
;                     for (int r = 0; r < 16; ++r) { const float p = __builtin_amdgcn_exp2f(st[kvh][r] - mrun); st[kvh][r] = p; ps += p; }
;                 lrun += ps;
;                 bf16x8 pf[4];
; #pragma unroll
;                 for (int ks = 0; ks < 4; ++ks) { const int kvh = ks >> 1, rb = 8 * (ks & 1); u32x4 w;
;                     w.x = cvt_pk_bf16(st[kvh][rb + 0], st[kvh][rb + 1]); w.y = cvt_pk_bf16(st[kvh][rb + 2], st[kvh][rb + 3]); w.z = cvt_pk_bf16(st[kvh][rb + 4], st[kvh][rb + 5]); w.w = cvt_pk_bf16(st[kvh][rb + 6], st[kvh][rb + 7]);
;                     pf[ks] = __builtin_bit_cast(bf16x8, w); }
;                 __builtin_amdgcn_sched_barrier(0);
; #pragma unroll
;                 for (int i = 0; i < 16; ++i) { o[i & 3] = __builtin_amdgcn_mfma_f32_32x32x16_bf16(vq[i % 4], pf[i >> 2], o[i & 3], 0, 0, 0);
;                     if (i + 4 < 16) vq[i % 4] = MLA_VF(i + 4);
;                     __builtin_amdgcn_sched_barrier(0); }
.LBB0_287:
	v_sub_f32_e32 v80, v80, v237
	v_exp_f32_e32 v80, v80
	v_sub_f32_e32 v81, v81, v237
	v_exp_f32_e32 v81, v81
	v_sub_f32_e32 v82, v82, v237
	v_exp_f32_e32 v82, v82
	v_sub_f32_e32 v83, v83, v237
	v_exp_f32_e32 v83, v83
	v_sub_f32_e32 v84, v84, v237
	v_exp_f32_e32 v84, v84
	v_sub_f32_e32 v85, v85, v237
	v_sub_f32_e32 v64, v64, v237
	v_add_f32_e32 v238, v81, v80
	v_exp_f32_e32 v85, v85
	v_sub_f32_e32 v86, v86, v237
	v_exp_f32_e32 v239, v64
	v_sub_f32_e32 v64, v65, v237
	v_add_f32_e32 v238, v82, v238
	v_exp_f32_e32 v86, v86
	v_sub_f32_e32 v87, v87, v237
	v_exp_f32_e32 v240, v64
	v_sub_f32_e32 v64, v66, v237
	v_add_f32_e32 v238, v83, v238
	v_exp_f32_e32 v87, v87
	v_sub_f32_e32 v88, v88, v237
	v_exp_f32_e32 v241, v64
	v_sub_f32_e32 v64, v67, v237
	v_add_f32_e32 v238, v84, v238
	v_exp_f32_e32 v88, v88
	v_sub_f32_e32 v89, v89, v237
	v_exp_f32_e32 v242, v64
	v_sub_f32_e32 v64, v68, v237
	v_add_f32_e32 v238, v85, v238
	v_exp_f32_e32 v89, v89
	v_sub_f32_e32 v90, v90, v237
	v_exp_f32_e32 v243, v64
	v_sub_f32_e32 v64, v69, v237
	v_add_f32_e32 v238, v86, v238
	v_exp_f32_e32 v90, v90
	v_sub_f32_e32 v91, v91, v237
	v_exp_f32_e32 v244, v64
	v_sub_f32_e32 v64, v70, v237
	v_add_f32_e32 v238, v87, v238
	v_exp_f32_e32 v91, v91
	v_sub_f32_e32 v92, v92, v237
	v_exp_f32_e32 v245, v64
	v_sub_f32_e32 v64, v71, v237
	v_add_f32_e32 v238, v88, v238
	v_exp_f32_e32 v92, v92
	v_sub_f32_e32 v93, v93, v237
	v_exp_f32_e32 v246, v64
	v_sub_f32_e32 v64, v72, v237
	v_add_f32_e32 v238, v89, v238
	v_exp_f32_e32 v93, v93
	v_sub_f32_e32 v94, v94, v237
	v_exp_f32_e32 v247, v64
	v_sub_f32_e32 v64, v73, v237
	v_add_f32_e32 v238, v90, v238
	v_exp_f32_e32 v94, v94
	v_sub_f32_e32 v95, v95, v237
	v_exp_f32_e32 v248, v64
	v_sub_f32_e32 v64, v74, v237
	v_add_f32_e32 v238, v91, v238
	v_exp_f32_e32 v95, v95
	v_exp_f32_e32 v249, v64
	v_sub_f32_e32 v64, v75, v237
	v_add_f32_e32 v238, v92, v238
	v_exp_f32_e32 v250, v64
	v_sub_f32_e32 v64, v76, v237
	v_add_f32_e32 v238, v93, v238
	v_exp_f32_e32 v251, v64
	v_sub_f32_e32 v64, v77, v237
	v_add_f32_e32 v238, v94, v238
	v_exp_f32_e32 v252, v64
	v_sub_f32_e32 v64, v78, v237
	v_add_f32_e32 v238, v95, v238
	v_exp_f32_e32 v253, v64
	v_sub_f32_e32 v64, v79, v237
	v_exp_f32_e32 v237, v64
	v_cvt_pk_bf16_f32 v64, v80, v81
	v_add_f32_e32 v80, v239, v238
	v_add_f32_e32 v80, v240, v80
	v_add_f32_e32 v80, v241, v80
	v_add_f32_e32 v80, v242, v80
	v_add_f32_e32 v80, v243, v80
	v_add_f32_e32 v80, v244, v80
	v_add_f32_e32 v80, v245, v80
	v_add_f32_e32 v80, v246, v80
	v_add_f32_e32 v80, v247, v80
	v_add_f32_e32 v80, v248, v80
	v_add_f32_e32 v80, v249, v80
	v_add_f32_e32 v80, v250, v80
	v_add_f32_e32 v80, v251, v80
	v_add_f32_e32 v80, v252, v80
	v_add_f32_e32 v80, v253, v80
	v_cvt_pk_bf16_f32 v65, v82, v83
	v_cvt_pk_bf16_f32 v66, v84, v85
	v_cvt_pk_bf16_f32 v67, v86, v87
	v_cvt_pk_bf16_f32 v68, v88, v89
	v_cvt_pk_bf16_f32 v69, v90, v91
	v_cvt_pk_bf16_f32 v70, v92, v93
	v_cvt_pk_bf16_f32 v71, v94, v95
	v_cvt_pk_bf16_f32 v72, v239, v240
	v_cvt_pk_bf16_f32 v73, v241, v242
	v_cvt_pk_bf16_f32 v74, v243, v244
	v_cvt_pk_bf16_f32 v75, v245, v246
	v_cvt_pk_bf16_f32 v76, v247, v248
	v_cvt_pk_bf16_f32 v77, v249, v250
	v_cvt_pk_bf16_f32 v78, v251, v252
	v_cvt_pk_bf16_f32 v79, v253, v237
	v_add_f32_e32 v92, v237, v80
	s_waitcnt lgkmcnt(3)
	v_mfma_f32_32x32x16_bf16 v[48:63], v[176:179], v[64:67], v[48:63]
	ds_read_b128 v[80:83], v236 offset:25632
	s_waitcnt lgkmcnt(3)
	v_mfma_f32_32x32x16_bf16 v[32:47], v[172:175], v[64:67], v[32:47]
	ds_read_b128 v[84:87], v236 offset:30240
	s_waitcnt lgkmcnt(3)
	v_mfma_f32_32x32x16_bf16 v[16:31], v[168:171], v[64:67], v[16:31]
	ds_read_b128 v[88:91], v236 offset:34848
	s_waitcnt lgkmcnt(3)
	v_mfma_f32_32x32x16_bf16 v[0:15], v[164:167], v[64:67], v[0:15]
	ds_read_b128 v[64:67], v236 offset:39456
	s_waitcnt lgkmcnt(3)
	v_mfma_f32_32x32x16_bf16 v[48:63], v[80:83], v[68:71], v[48:63]
	ds_read_b128 v[80:83], v236 offset:25664
	s_waitcnt lgkmcnt(3)
	v_mfma_f32_32x32x16_bf16 v[32:47], v[84:87], v[68:71], v[32:47]
	ds_read_b128 v[84:87], v236 offset:30272
	s_waitcnt lgkmcnt(3)
	v_mfma_f32_32x32x16_bf16 v[16:31], v[88:91], v[68:71], v[16:31]
	ds_read_b128 v[88:91], v236 offset:34880
	s_waitcnt lgkmcnt(3)
	v_mfma_f32_32x32x16_bf16 v[0:15], v[64:67], v[68:71], v[0:15]
	ds_read_b128 v[64:67], v236 offset:39488
	s_waitcnt lgkmcnt(3)
	v_mfma_f32_32x32x16_bf16 v[48:63], v[80:83], v[72:75], v[48:63]
	ds_read_b128 v[68:71], v236 offset:25696
	s_waitcnt lgkmcnt(3)
	v_mfma_f32_32x32x16_bf16 v[32:47], v[84:87], v[72:75], v[32:47]
	ds_read_b128 v[80:83], v236 offset:30304
	s_waitcnt lgkmcnt(3)
	v_mfma_f32_32x32x16_bf16 v[16:31], v[88:91], v[72:75], v[16:31]
	ds_read_b128 v[84:87], v236 offset:34912
	s_waitcnt lgkmcnt(3)
	v_mfma_f32_32x32x16_bf16 v[0:15], v[64:67], v[72:75], v[0:15]
	ds_read_b128 v[64:67], v236 offset:39520
	s_waitcnt lgkmcnt(3)
	v_mfma_f32_32x32x16_bf16 v[48:63], v[68:71], v[76:79], v[48:63]
	s_waitcnt lgkmcnt(2)
	v_mfma_f32_32x32x16_bf16 v[32:47], v[80:83], v[76:79], v[32:47]
	s_waitcnt lgkmcnt(1)
	v_mfma_f32_32x32x16_bf16 v[16:31], v[84:87], v[76:79], v[16:31]
	s_waitcnt lgkmcnt(0)
	v_mfma_f32_32x32x16_bf16 v[0:15], v[64:67], v[76:79], v[0:15]
	v_add_f32_e32 v201, v201, v92
	s_andn2_b64 vcc, exec, s[30:31]
	s_cbranch_vccz .LBB0_278
	s_branch .LBB0_279
